# fin phase: the per-thread ml_norm weights are loaded once per iteration into spare registers instead of once per item behind a full wait
# speedup vs baseline: 1.0079x; 1.0079x over previous
; __device__ __forceinline__ int opaque_tid(int wv) { asm volatile("" : "+s"(wv)); unsigned z = 0u; asm volatile("" : "+v"(z)); const int l = __builtin_amdgcn_mbcnt_hi(~0u, __builtin_amdgcn_mbcnt_lo(~0u, z)); return (wv << 6) | l; }
; __device__ __forceinline__ int opaque_bid() { int t = blockIdx.x; asm volatile("" : "+s"(t)); return t; }
; __device__ __forceinline__ unsigned pack2(float lo, float hi) { unsigned r; asm("v_cvt_pk_bf16_f32 %0, %1, %2" : "=v"(r) : "v"(lo), "v"(hi)); return r; }
; __device__ __forceinline__ float lo16(unsigned w) { return __uint_as_float(w << 16); }
; __device__ __forceinline__ float hi16(unsigned w) { return __uint_as_float(w & 0xffff0000u); }
; __device__ __forceinline__ float sigm(float x) { return __builtin_amdgcn_rcpf(1.0f + __expf(-x)); }
; __device__ __forceinline__ void fin_phase(int wv, PP P, int L) {
;     ...
;     for (int idx0 = opaque_bid() * 512 + opaque_tid(wv); idx0 < total; idx0 += 4 * nthr) {
;         u32x4 raw[4], og[4]; float rr[4];
; #pragma unroll
;         for (int k = 0; k < 4; ++k) { const int idx = idx0 + k * nthr; if (idx < total) { const int row = idx >> 7, c = (idx & 127) * 8;
;             raw[k] = *(const u32x4*)(cat + (size_t)row * D + 512 + c); og[k] = *(const u32x4*)(zA + (size_t)row * NZA + ZA_MO + c); rr[k] = hsq[(size_t)row * 4 + (c >> 8)]; } }
; #pragma unroll
;         for (int k = 0; k < 4; ++k) { const int idx = idx0 + k * nthr; if (idx < total) { const int row = idx >> 7, c = (idx & 127) * 8;
;             const float r = rsqrtf(rr[k] * (1.0f / 256.0f) + EPS); const f32x4 w0 = *(const f32x4*)(mn + c), w1 = *(const f32x4*)(mn + c + 4); u32x4 o;
;             o.x = pack2(lo16(raw[k].x) * r * w0[0] * sigm(lo16(og[k].x)), hi16(raw[k].x) * r * w0[1] * sigm(hi16(og[k].x)));
;             o.y = pack2(lo16(raw[k].y) * r * w0[2] * sigm(lo16(og[k].y)), hi16(raw[k].y) * r * w0[3] * sigm(hi16(og[k].y)));
;             o.z = pack2(lo16(raw[k].z) * r * w1[0] * sigm(lo16(og[k].z)), hi16(raw[k].z) * r * w1[1] * sigm(hi16(og[k].z)));
;             o.w = pack2(lo16(raw[k].w) * r * w1[2] * sigm(lo16(og[k].w)), hi16(raw[k].w) * r * w1[3] * sigm(hi16(og[k].w)));
;             *(u32x4*)(cat + (size_t)row * D + 512 + c) = o; } }
.LBB0_454:
	s_or_b64 exec, exec, s[22:23]
	v_lshlrev_b32_e32 v42, 2, v49
	global_load_dwordx4 v[240:243], v42, s[18:19]
	global_load_dwordx4 v[244:247], v42, s[18:19] offset:16
	global_load_dwordx4 v[52:55], v42, s[18:19]
	global_load_dwordx4 v[56:59], v42, s[18:19] offset:16
	v_mov_b32_e32 v43, v3
	s_waitcnt vmcnt(2)
	v_fmamk_f32 v49, v50, 0x3b800000, v220
	v_lshlrev_b32_e32 v51, 16, v32
	v_and_b32_e32 v32, 0xffff0000, v32
	v_lshlrev_b32_e32 v61, 16, v33
	v_and_b32_e32 v33, 0xffff0000, v33
	v_lshlrev_b32_e32 v63, 16, v34
	v_and_b32_e32 v64, 0xffff0000, v34
	v_lshlrev_b32_e32 v66, 16, v35
	v_and_b32_e32 v67, 0xffff0000, v35
	v_lshl_add_u64 v[34:35], s[18:19], 0, v[42:43]
	v_mul_f32_e32 v42, 0x4b800000, v49
	v_mul_f32_e32 v43, 0xbfb8aa3b, v51
	v_mul_f32_e32 v32, 0xbfb8aa3b, v32
	v_mul_f32_e32 v51, 0xbfb8aa3b, v61
	v_mul_f32_e32 v33, 0xbfb8aa3b, v33
	v_mul_f32_e32 v61, 0xbfb8aa3b, v63
	v_mul_f32_e32 v63, 0xbfb8aa3b, v64
	v_mul_f32_e32 v64, 0xbfb8aa3b, v66
	v_mul_f32_e32 v66, 0xbfb8aa3b, v67
	v_cmp_gt_f32_e32 vcc, s96, v49
	v_exp_f32_e32 v32, v32
	v_exp_f32_e32 v33, v33
	v_cndmask_b32_e32 v42, v49, v42, vcc
	v_exp_f32_e32 v49, v51
	v_exp_f32_e32 v51, v61
	v_exp_f32_e32 v61, v63
	v_exp_f32_e32 v63, v64
	v_exp_f32_e32 v64, v66
	v_exp_f32_e32 v43, v43
	v_rsq_f32_e32 v42, v42
	v_add_f32_e32 v32, 1.0, v32
	v_add_f32_e32 v33, 1.0, v33
	v_add_f32_e32 v61, 1.0, v61
	v_add_f32_e32 v64, 1.0, v64
	v_add_f32_e32 v43, 1.0, v43
	v_add_f32_e32 v49, 1.0, v49
	v_add_f32_e32 v51, 1.0, v51
	v_add_f32_e32 v63, 1.0, v63
	v_mul_f32_e32 v66, 0x45800000, v42
	v_rcp_f32_e32 v32, v32
	v_rcp_f32_e32 v33, v33
	v_rcp_f32_e32 v61, v61
	v_rcp_f32_e32 v64, v64
	v_lshlrev_b32_e32 v50, 16, v28
	v_and_b32_e32 v28, 0xffff0000, v28
	v_lshlrev_b32_e32 v60, 16, v29
	v_and_b32_e32 v29, 0xffff0000, v29
	v_lshlrev_b32_e32 v62, 16, v30
	v_and_b32_e32 v30, 0xffff0000, v30
	v_lshlrev_b32_e32 v65, 16, v31
	v_and_b32_e32 v31, 0xffff0000, v31
	v_rcp_f32_e32 v43, v43
	v_rcp_f32_e32 v49, v49
	v_rcp_f32_e32 v51, v51
	v_rcp_f32_e32 v63, v63
	v_cndmask_b32_e32 v42, v42, v66, vcc
	v_mul_f32_e32 v28, v42, v28
	v_mul_f32_e32 v29, v42, v29
	v_mul_f32_e32 v30, v42, v30
	v_mul_f32_e32 v31, v42, v31
	v_mul_f32_e32 v50, v42, v50
	v_mul_f32_e32 v60, v42, v60
	v_mul_f32_e32 v62, v42, v62
	v_mul_f32_e32 v65, v42, v65
	s_waitcnt vmcnt(1)
	v_mul_f32_e32 v28, v53, v28
	v_mul_f32_e32 v29, v55, v29
	s_waitcnt vmcnt(0)
	v_mul_f32_e32 v30, v57, v30
	v_mul_f32_e32 v31, v59, v31
	v_mul_f32_e32 v50, v52, v50
	v_mul_f32_e32 v52, v54, v60
	v_mul_f32_e32 v53, v56, v62
	v_mul_f32_e32 v54, v58, v65
	v_mul_f32_e32 v28, v28, v32
	v_mul_f32_e32 v29, v29, v33
	v_mul_f32_e32 v30, v30, v61
	v_mul_f32_e32 v31, v31, v64
	v_mul_f32_e32 v43, v50, v43
	v_mul_f32_e32 v32, v52, v49
	v_mul_f32_e32 v33, v53, v51
	v_mul_f32_e32 v49, v54, v63
	v_cvt_pk_bf16_f32 v28, v43, v28
	v_cvt_pk_bf16_f32 v29, v32, v29
	v_cvt_pk_bf16_f32 v30, v33, v30
	v_cvt_pk_bf16_f32 v31, v49, v31
	global_store_dwordx4 v[40:41], v[28:31], off offset:1024
	s_and_saveexec_b64 s[22:23], s[8:9]
	s_cbranch_execnz .LBB0_457
	s_or_b64 exec, exec, s[22:23]
	s_and_saveexec_b64 s[8:9], s[6:7]
	s_cbranch_execnz .LBB0_458

; __device__ __forceinline__ unsigned pack2(float lo, float hi) { unsigned r; asm("v_cvt_pk_bf16_f32 %0, %1, %2" : "=v"(r) : "v"(lo), "v"(hi)); return r; }
; __device__ __forceinline__ float lo16(unsigned w) { return __uint_as_float(w << 16); }
; __device__ __forceinline__ float hi16(unsigned w) { return __uint_as_float(w & 0xffff0000u); }
; __device__ __forceinline__ float sigm(float x) { return __builtin_amdgcn_rcpf(1.0f + __expf(-x)); }
; __device__ __forceinline__ void fin_phase(int wv, PP P, int L) {
;     ...
;         for (int k = 0; k < 4; ++k) { const int idx = idx0 + k * nthr; if (idx < total) { const int row = idx >> 7, c = (idx & 127) * 8;
;             const float r = rsqrtf(rr[k] * (1.0f / 256.0f) + EPS); const f32x4 w0 = *(const f32x4*)(mn + c), w1 = *(const f32x4*)(mn + c + 4); u32x4 o;
;             o.x = pack2(lo16(raw[k].x) * r * w0[0] * sigm(lo16(og[k].x)), hi16(raw[k].x) * r * w0[1] * sigm(hi16(og[k].x)));
;             o.y = pack2(lo16(raw[k].y) * r * w0[2] * sigm(lo16(og[k].y)), hi16(raw[k].y) * r * w0[3] * sigm(hi16(og[k].y)));
;             o.z = pack2(lo16(raw[k].z) * r * w1[0] * sigm(lo16(og[k].z)), hi16(raw[k].z) * r * w1[1] * sigm(hi16(og[k].z)));
;             o.w = pack2(lo16(raw[k].w) * r * w1[2] * sigm(lo16(og[k].w)), hi16(raw[k].w) * r * w1[3] * sigm(hi16(og[k].w)));
;             *(u32x4*)(cat + (size_t)row * D + 512 + c) = o; } }
.LBB0_457:
	v_fmamk_f32 v28, v46, 0x3b800000, v220
	v_cmp_gt_f32_e32 vcc, s96, v28
	v_mul_f32_e32 v29, 0x4b800000, v28
	s_nop 0
	v_cndmask_b32_e32 v28, v28, v29, vcc
	v_rsq_f32_e32 v28, v28
	s_nop 0
	v_mul_f32_e32 v29, 0x45800000, v28
	v_cndmask_b32_e32 v49, v28, v29, vcc
	v_lshlrev_b32_e32 v29, 16, v16
	v_lshlrev_b32_e32 v28, 16, v4
	v_mul_f32_e32 v29, 0xbfb8aa3b, v29
	v_mul_f32_e32 v28, v49, v28
	v_exp_f32_e32 v29, v29
	v_mul_f32_e32 v28, v28, v240
	v_and_b32_e32 v40, 0xffff0000, v16
	v_mul_f32_e32 v40, 0xbfb8aa3b, v40
	v_exp_f32_e32 v40, v40
	v_add_f32_e32 v29, 1.0, v29
	v_rcp_f32_e32 v29, v29
	v_add_f32_e32 v40, 1.0, v40
	v_rcp_f32_e32 v40, v40
	v_mul_f32_e32 v28, v29, v28
	v_and_b32_e32 v29, 0xffff0000, v4
	v_mul_f32_e32 v29, v49, v29
	v_mul_f32_e32 v29, v29, v241
	v_mul_f32_e32 v29, v40, v29
	v_lshlrev_b32_e32 v40, 16, v17
	v_mul_f32_e32 v40, 0xbfb8aa3b, v40
	v_exp_f32_e32 v40, v40
	v_and_b32_e32 v41, 0xffff0000, v17
	v_mul_f32_e32 v41, 0xbfb8aa3b, v41
	v_exp_f32_e32 v41, v41
	v_add_f32_e32 v40, 1.0, v40
	v_rcp_f32_e32 v40, v40
	v_cvt_pk_bf16_f32 v28, v28, v29
	v_lshlrev_b32_e32 v29, 16, v5
	v_mul_f32_e32 v29, v49, v29
	v_add_f32_e32 v41, 1.0, v41
	v_mul_f32_e32 v29, v29, v242
	v_rcp_f32_e32 v41, v41
	v_mul_f32_e32 v29, v40, v29
	v_and_b32_e32 v40, 0xffff0000, v5
	v_mul_f32_e32 v40, v49, v40
	v_mul_f32_e32 v40, v40, v243
	v_mul_f32_e32 v40, v41, v40
	v_cvt_pk_bf16_f32 v29, v29, v40
	v_lshlrev_b32_e32 v40, 16, v6
	v_mul_f32_e32 v40, v49, v40
	v_mul_f32_e32 v30, v40, v244
	v_lshlrev_b32_e32 v40, 16, v18
	v_mul_f32_e32 v40, 0xbfb8aa3b, v40
	v_exp_f32_e32 v40, v40
	s_nop 0
	v_add_f32_e32 v40, 1.0, v40
	v_rcp_f32_e32 v40, v40
	s_nop 0
	v_mul_f32_e32 v30, v40, v30
	v_and_b32_e32 v40, 0xffff0000, v6
	v_mul_f32_e32 v40, v49, v40
	v_mul_f32_e32 v31, v40, v245
	v_and_b32_e32 v40, 0xffff0000, v18
	v_mul_f32_e32 v40, 0xbfb8aa3b, v40
	v_exp_f32_e32 v40, v40
	s_nop 0
	v_add_f32_e32 v40, 1.0, v40
	v_rcp_f32_e32 v40, v40
	s_nop 0
	v_mul_f32_e32 v31, v40, v31
	v_cvt_pk_bf16_f32 v30, v30, v31
	v_lshlrev_b32_e32 v31, 16, v7
	v_mul_f32_e32 v31, v49, v31
	v_mul_f32_e32 v31, v31, v246
	v_lshlrev_b32_e32 v32, 16, v19
	v_mul_f32_e32 v32, 0xbfb8aa3b, v32
	v_exp_f32_e32 v32, v32
	s_nop 0
	v_add_f32_e32 v32, 1.0, v32
	v_rcp_f32_e32 v32, v32
	s_nop 0
	v_mul_f32_e32 v31, v32, v31
	v_and_b32_e32 v32, 0xffff0000, v7
	v_mul_f32_e32 v32, v49, v32
	v_mul_f32_e32 v32, v32, v247
	v_and_b32_e32 v33, 0xffff0000, v19
	v_mul_f32_e32 v33, 0xbfb8aa3b, v33
	v_exp_f32_e32 v33, v33
	s_nop 0
	v_add_f32_e32 v33, 1.0, v33
	v_rcp_f32_e32 v33, v33
	s_nop 0
	v_mul_f32_e32 v32, v33, v32
	v_cvt_pk_bf16_f32 v31, v31, v32
	v_lshlrev_b64 v[32:33], 12, v[38:39]
	v_lshl_add_u64 v[32:33], s[12:13], 0, v[32:33]
	v_lshl_add_u64 v[32:33], v[32:33], 0, v[2:3]
	global_store_dwordx4 v[32:33], v[28:31], off offset:1024
	s_or_b64 exec, exec, s[22:23]
	s_and_saveexec_b64 s[8:9], s[6:7]
	s_cbranch_execz .LBB0_456
; __device__ __forceinline__ unsigned pack2(float lo, float hi) { unsigned r; asm("v_cvt_pk_bf16_f32 %0, %1, %2" : "=v"(r) : "v"(lo), "v"(hi)); return r; }
; __device__ __forceinline__ float lo16(unsigned w) { return __uint_as_float(w << 16); }
; __device__ __forceinline__ float hi16(unsigned w) { return __uint_as_float(w & 0xffff0000u); }
; __device__ __forceinline__ float sigm(float x) { return __builtin_amdgcn_rcpf(1.0f + __expf(-x)); }
; __device__ __forceinline__ void fin_phase(int wv, PP P, int L) {
;     ...
;         for (int k = 0; k < 4; ++k) { const int idx = idx0 + k * nthr; if (idx < total) { const int row = idx >> 7, c = (idx & 127) * 8;
;             const float r = rsqrtf(rr[k] * (1.0f / 256.0f) + EPS); const f32x4 w0 = *(const f32x4*)(mn + c), w1 = *(const f32x4*)(mn + c + 4); u32x4 o;
;             o.x = pack2(lo16(raw[k].x) * r * w0[0] * sigm(lo16(og[k].x)), hi16(raw[k].x) * r * w0[1] * sigm(hi16(og[k].x)));
;             o.y = pack2(lo16(raw[k].y) * r * w0[2] * sigm(lo16(og[k].y)), hi16(raw[k].y) * r * w0[3] * sigm(hi16(og[k].y)));
;             o.z = pack2(lo16(raw[k].z) * r * w1[0] * sigm(lo16(og[k].z)), hi16(raw[k].z) * r * w1[1] * sigm(hi16(og[k].z)));
;             o.w = pack2(lo16(raw[k].w) * r * w1[2] * sigm(lo16(og[k].w)), hi16(raw[k].w) * r * w1[3] * sigm(hi16(og[k].w)));
;             *(u32x4*)(cat + (size_t)row * D + 512 + c) = o; } }
.LBB0_458:
	v_fmamk_f32 v28, v47, 0x3b800000, v220
	v_cmp_gt_f32_e32 vcc, s96, v28
	v_mul_f32_e32 v29, 0x4b800000, v28
	s_nop 0
	v_cndmask_b32_e32 v28, v28, v29, vcc
	v_rsq_f32_e32 v28, v28
	s_nop 0
	v_mul_f32_e32 v29, 0x45800000, v28
	v_cndmask_b32_e32 v42, v28, v29, vcc
	v_lshlrev_b32_e32 v29, 16, v20
	v_lshlrev_b32_e32 v28, 16, v8
	v_mul_f32_e32 v29, 0xbfb8aa3b, v29
	v_mul_f32_e32 v28, v42, v28
	v_exp_f32_e32 v29, v29
	v_mul_f32_e32 v28, v28, v240
	v_and_b32_e32 v38, 0xffff0000, v20
	v_mul_f32_e32 v38, 0xbfb8aa3b, v38
	v_exp_f32_e32 v38, v38
	v_add_f32_e32 v29, 1.0, v29
	v_rcp_f32_e32 v29, v29
	v_add_f32_e32 v38, 1.0, v38
	v_rcp_f32_e32 v38, v38
	v_mul_f32_e32 v28, v29, v28
	v_and_b32_e32 v29, 0xffff0000, v8
	v_mul_f32_e32 v29, v42, v29
	v_mul_f32_e32 v29, v29, v241
	v_mul_f32_e32 v29, v38, v29
	v_lshlrev_b32_e32 v38, 16, v21
	v_mul_f32_e32 v38, 0xbfb8aa3b, v38
	v_exp_f32_e32 v38, v38
	v_and_b32_e32 v39, 0xffff0000, v21
	v_mul_f32_e32 v39, 0xbfb8aa3b, v39
	v_exp_f32_e32 v39, v39
	v_add_f32_e32 v38, 1.0, v38
	v_rcp_f32_e32 v38, v38
	v_cvt_pk_bf16_f32 v28, v28, v29
	v_lshlrev_b32_e32 v29, 16, v9
	v_mul_f32_e32 v29, v42, v29
	v_add_f32_e32 v39, 1.0, v39
	v_mul_f32_e32 v29, v29, v242
	v_rcp_f32_e32 v39, v39
	v_mul_f32_e32 v29, v38, v29
	v_and_b32_e32 v38, 0xffff0000, v9
	v_mul_f32_e32 v38, v42, v38
	v_mul_f32_e32 v38, v38, v243
	v_mul_f32_e32 v38, v39, v38
	v_cvt_pk_bf16_f32 v29, v29, v38
	v_lshlrev_b32_e32 v38, 16, v10
	v_mul_f32_e32 v38, v42, v38
	v_mul_f32_e32 v30, v38, v244
	v_lshlrev_b32_e32 v38, 16, v22
	v_mul_f32_e32 v38, 0xbfb8aa3b, v38
	v_exp_f32_e32 v38, v38
	s_nop 0
	v_add_f32_e32 v38, 1.0, v38
	v_rcp_f32_e32 v38, v38
	s_nop 0
	v_mul_f32_e32 v30, v38, v30
	v_and_b32_e32 v38, 0xffff0000, v10
	v_mul_f32_e32 v38, v42, v38
	v_mul_f32_e32 v31, v38, v245
	v_and_b32_e32 v38, 0xffff0000, v22
	v_mul_f32_e32 v38, 0xbfb8aa3b, v38
	v_exp_f32_e32 v38, v38
	s_nop 0
	v_add_f32_e32 v38, 1.0, v38
	v_rcp_f32_e32 v38, v38
	s_nop 0
	v_mul_f32_e32 v31, v38, v31
	v_cvt_pk_bf16_f32 v30, v30, v31
	v_lshlrev_b32_e32 v31, 16, v11
	v_mul_f32_e32 v31, v42, v31
	v_mul_f32_e32 v31, v31, v246
	v_lshlrev_b32_e32 v32, 16, v23
	v_mul_f32_e32 v32, 0xbfb8aa3b, v32
	v_exp_f32_e32 v32, v32
	s_nop 0
	v_add_f32_e32 v32, 1.0, v32
	v_rcp_f32_e32 v32, v32
	s_nop 0
	v_mul_f32_e32 v31, v32, v31
	v_and_b32_e32 v32, 0xffff0000, v11
	v_mul_f32_e32 v32, v42, v32
	v_mul_f32_e32 v32, v32, v247
	v_and_b32_e32 v33, 0xffff0000, v23
	v_mul_f32_e32 v33, 0xbfb8aa3b, v33
	v_exp_f32_e32 v33, v33
	s_nop 0
	v_add_f32_e32 v33, 1.0, v33
	v_rcp_f32_e32 v33, v33
	s_nop 0
	v_mul_f32_e32 v32, v33, v32
	v_cvt_pk_bf16_f32 v31, v31, v32
	v_lshlrev_b64 v[32:33], 12, v[36:37]
	v_lshl_add_u64 v[32:33], s[12:13], 0, v[32:33]
	v_lshl_add_u64 v[32:33], v[32:33], 0, v[2:3]
	global_store_dwordx4 v[32:33], v[28:31], off offset:1024
	s_or_b64 exec, exec, s[8:9]
	s_and_saveexec_b64 s[6:7], s[4:5]
	s_cbranch_execz .LBB0_447
.LBB0_459:
	s_nop 0
	v_fmamk_f32 v28, v45, 0x3b800000, v220
	v_cmp_gt_f32_e32 vcc, s96, v28
	v_mul_f32_e32 v29, 0x4b800000, v28
	v_lshlrev_b64 v[0:1], 12, v[0:1]
	v_cndmask_b32_e32 v28, v28, v29, vcc
	v_rsq_f32_e32 v28, v28
	v_lshl_add_u64 v[0:1], s[12:13], 0, v[0:1]
	v_lshl_add_u64 v[0:1], v[0:1], 0, v[2:3]
	v_mul_f32_e32 v29, 0x45800000, v28
	v_cndmask_b32_e32 v38, v28, v29, vcc
	v_lshlrev_b32_e32 v29, 16, v24
	v_lshlrev_b32_e32 v28, 16, v12
	v_mul_f32_e32 v29, 0xbfb8aa3b, v29
	v_mul_f32_e32 v28, v38, v28
	v_exp_f32_e32 v29, v29
	v_mul_f32_e32 v28, v28, v240
	v_and_b32_e32 v34, 0xffff0000, v24
	v_mul_f32_e32 v34, 0xbfb8aa3b, v34
	v_exp_f32_e32 v34, v34
	v_add_f32_e32 v29, 1.0, v29
	v_rcp_f32_e32 v29, v29
	v_add_f32_e32 v34, 1.0, v34
	v_rcp_f32_e32 v34, v34
	v_mul_f32_e32 v28, v29, v28
	v_and_b32_e32 v29, 0xffff0000, v12
	v_mul_f32_e32 v29, v38, v29
	v_mul_f32_e32 v29, v29, v241
	v_mul_f32_e32 v29, v34, v29
	v_lshlrev_b32_e32 v34, 16, v25
	v_mul_f32_e32 v34, 0xbfb8aa3b, v34
	v_exp_f32_e32 v34, v34
	v_and_b32_e32 v35, 0xffff0000, v25
	v_mul_f32_e32 v35, 0xbfb8aa3b, v35
	v_exp_f32_e32 v35, v35
	v_add_f32_e32 v34, 1.0, v34
	v_rcp_f32_e32 v34, v34
	v_cvt_pk_bf16_f32 v28, v28, v29
	v_lshlrev_b32_e32 v29, 16, v13
	v_mul_f32_e32 v29, v38, v29
	v_add_f32_e32 v35, 1.0, v35
	v_mul_f32_e32 v29, v29, v242
	v_rcp_f32_e32 v35, v35
	v_mul_f32_e32 v29, v34, v29
	v_and_b32_e32 v34, 0xffff0000, v13
	v_mul_f32_e32 v34, v38, v34
	v_mul_f32_e32 v34, v34, v243
	v_mul_f32_e32 v34, v35, v34
	v_cvt_pk_bf16_f32 v29, v29, v34
	v_lshlrev_b32_e32 v34, 16, v14
	v_mul_f32_e32 v34, v38, v34
	v_mul_f32_e32 v30, v34, v244
	v_lshlrev_b32_e32 v34, 16, v26
	v_mul_f32_e32 v34, 0xbfb8aa3b, v34
	v_exp_f32_e32 v34, v34
	s_nop 0
	v_add_f32_e32 v34, 1.0, v34
	v_rcp_f32_e32 v34, v34
	s_nop 0
	v_mul_f32_e32 v30, v34, v30
	v_and_b32_e32 v34, 0xffff0000, v14
	v_mul_f32_e32 v34, v38, v34
	v_mul_f32_e32 v31, v34, v245
	v_and_b32_e32 v34, 0xffff0000, v26
	v_mul_f32_e32 v34, 0xbfb8aa3b, v34
	v_exp_f32_e32 v34, v34
	s_nop 0
	v_add_f32_e32 v34, 1.0, v34
	v_rcp_f32_e32 v34, v34
	s_nop 0
	v_mul_f32_e32 v31, v34, v31
	v_cvt_pk_bf16_f32 v30, v30, v31
	v_lshlrev_b32_e32 v31, 16, v15
	v_mul_f32_e32 v31, v38, v31
	v_mul_f32_e32 v31, v31, v246
	v_lshlrev_b32_e32 v32, 16, v27
	v_mul_f32_e32 v32, 0xbfb8aa3b, v32
	v_exp_f32_e32 v32, v32
	s_nop 0
	v_add_f32_e32 v32, 1.0, v32
	v_rcp_f32_e32 v32, v32
	s_nop 0
	v_mul_f32_e32 v31, v32, v31
	v_and_b32_e32 v32, 0xffff0000, v15
	v_mul_f32_e32 v32, v38, v32
	v_mul_f32_e32 v32, v32, v247
	v_and_b32_e32 v33, 0xffff0000, v27
	v_mul_f32_e32 v33, 0xbfb8aa3b, v33
	v_exp_f32_e32 v33, v33
	s_nop 0
	v_add_f32_e32 v33, 1.0, v33
	v_rcp_f32_e32 v33, v33
	s_nop 0
	v_mul_f32_e32 v32, v33, v32
	v_cvt_pk_bf16_f32 v31, v31, v32
	global_store_dwordx4 v[0:1], v[28:31], off offset:1024
	s_branch .LBB0_447
